# overlap v4: 16 row-group counters, write-through GEMM stores for the overlapped phase, one polling wave per workgroup, weight conversion spread over 192 workgroups
# speedup vs baseline: 1.0343x; 1.0159x over previous
.LBB0_124:
	s_mov_b32 s98, 0
	s_sub_u32 s4, s3, 64
	s_cmpk_lt_u32 s4, 0x1000
	s_cbranch_scc0 .Lmap_smp_first
	s_lshr_b32 s5, s4, 8
	s_lshl_b32 s5, s5, 1
	s_and_b32 s9, s4, 7
	s_lshl_b32 s9, s9, 5
	s_add_u32 s9, s9, s5
	s_bfe_u32 s5, s4, 0x10003
	s_add_u32 s8, s9, s5
	s_bfe_u32 s81, s4, 0x40004
	s_branch .Lmap_done_first

.LBB0_131:
.Lsig_check:
	s_cmp_gt_u32 s98, 15
	s_cbranch_scc1 .Lsig_end
	s_cmp_lg_u64 s[4:5], 0
	s_cbranch_scc1 .Lsig_last
	s_add_u32 s99, s98, 1
	s_lshl_b32 s99, s99, 8
	s_sub_u32 s99, s99, 1
	s_mul_i32 s99, s99, 0xaaab
	s_lshr_b32 s99, s99, 23
	s_add_u32 s99, s99, 2
	s_cmp_ge_u32 s35, s99
	s_cbranch_scc0 .Lsig_end
	s_waitcnt vmcnt(24)
	s_branch .Lsig_go

.Lsig_go:
	s_barrier
	v_readfirstlane_b32 s99, v208
	s_lshr_b32 s99, s99, 6
	s_cmp_lg_u32 s99, 4
	s_cbranch_scc1 .Lsig_skipw
	s_lshl_b32 s99, s98, 6
	s_add_u32 s99, s99, 0x3800
	v_mov_b32_e32 v253, s99
	v_mov_b32_e32 v254, 1
	s_mov_b64 s[100:101], exec
	s_mov_b64 exec, 1
	global_atomic_add v253, v254, s[74:75]
	s_mov_b64 exec, s[100:101]

.LBB0_134:
	s_mul_i32 s4, s35, 0xc0
	s_add_u32 s4, s4, s3
	s_sub_u32 s4, s4, 64
	s_cmpk_lt_u32 s4, 0x1000
	s_cbranch_scc0 .Lmap_smp_next
	s_lshr_b32 s5, s4, 8
	s_lshl_b32 s5, s5, 1
	s_and_b32 s9, s4, 7
	s_lshl_b32 s9, s9, 5
	s_add_u32 s9, s9, s5
	s_bfe_u32 s5, s4, 0x10003
	s_add_u32 s20, s9, s5
	s_bfe_u32 s80, s4, 0x40004
	s_branch .Lmap_done_next

.LBB0_160:
	v_or_b32_e32 v136, s9, v178
	v_lshl_add_u32 v170, s8, 8, v176
	v_lshlrev_b32_e32 v160, 1, v136
	v_ashrrev_i32_e32 v171, 31, v170
	v_lshl_add_u64 v[172:173], s[38:39], 0, v[160:161]
	v_lshlrev_b64 v[136:137], 13, v[170:171]
	v_lshl_add_u64 v[174:175], v[172:173], 0, v[136:137]
	v_cvt_pk_bf16_f32 v136, v144, v145
	v_cvt_pk_bf16_f32 v137, v146, v147
	v_cvt_pk_bf16_f32 v138, v148, v149
	v_cvt_pk_bf16_f32 v139, v150, v151
	global_store_dwordx4 v[174:175], v[136:139], off sc1
	s_andn2_b64 vcc, exec, s[24:25]
	s_nop 0
	v_cndmask_b32_e64 v136, 0, 1, s[24:25]
	v_cmp_ne_u32_e64 s[8:9], 1, v136
	s_mov_b64 s[24:25], -1
	s_cbranch_vccnz .LBB0_164
	v_mov_b64_e32 v[142:143], v[130:131]
	v_mov_b64_e32 v[138:139], v[134:135]
	s_and_b64 vcc, exec, s[6:7]
	v_mov_b64_e32 v[140:141], v[128:129]
	v_mov_b64_e32 v[136:137], v[132:133]
	s_cbranch_vccnz .LBB0_163
	v_mul_f32_e32 v137, 0x3fb8aa3b, v128
	v_mul_f32_e32 v138, 0x3fb8aa3b, v133
	v_exp_f32_e32 v137, v137
	v_exp_f32_e32 v138, v138
	v_mul_f32_e32 v139, 0x3fb8aa3b, v134
	v_mul_f32_e32 v141, 0x3fb8aa3b, v130
	v_add_f32_e32 v137, 1.0, v137
	v_rcp_f32_e32 v140, v137
	v_add_f32_e32 v137, 1.0, v138
	v_mul_f32_e32 v138, 0x3fb8aa3b, v129
	v_exp_f32_e32 v138, v138
	v_exp_f32_e32 v139, v139
	v_exp_f32_e32 v141, v141
	v_mul_f32_e32 v136, 0x3fb8aa3b, v132
	v_add_f32_e32 v144, 1.0, v138
	v_add_f32_e32 v138, 1.0, v139
	v_add_f32_e32 v139, 1.0, v141
	v_mul_f32_e32 v141, 0x3fb8aa3b, v135
	v_mul_f32_e32 v142, 0x3fb8aa3b, v131
	v_exp_f32_e32 v136, v136
	v_exp_f32_e32 v141, v141
	v_exp_f32_e32 v143, v142
	v_rcp_f32_e32 v142, v139
	v_add_f32_e32 v136, 1.0, v136
	v_add_f32_e32 v139, 1.0, v141
	v_add_f32_e32 v141, 1.0, v143
	v_rcp_f32_e32 v136, v136
	v_rcp_f32_e32 v137, v137
	v_rcp_f32_e32 v138, v138
	v_rcp_f32_e32 v139, v139
	v_rcp_f32_e32 v143, v141
	v_rcp_f32_e32 v141, v144
	s_waitcnt vmcnt(0)
	v_pk_mul_f32 v[136:137], v[136:137], v[28:29]
	v_pk_mul_f32 v[138:139], v[138:139], v[30:31]
	v_pk_mul_f32 v[142:143], v[142:143], v[26:27]
	v_pk_mul_f32 v[140:141], v[140:141], v[24:25]

.LBB0_166:
	v_cvt_pk_bf16_f32 v128, v136, v137
	v_cvt_pk_bf16_f32 v129, v138, v139
	v_cvt_pk_bf16_f32 v130, v140, v141
	v_cvt_pk_bf16_f32 v131, v142, v143
	s_and_b64 vcc, exec, s[8:9]
	s_mov_b64 s[24:25], -1
	global_store_dwordx4 v[174:175], v[128:131], off offset:256 sc1
	s_cbranch_vccnz .LBB0_170
	v_mov_b64_e32 v[134:135], v[122:123]
	v_mov_b64_e32 v[130:131], v[126:127]
	s_and_b64 vcc, exec, s[6:7]
	v_mov_b64_e32 v[132:133], v[120:121]
	v_mov_b64_e32 v[128:129], v[124:125]
	s_cbranch_vccnz .LBB0_169
	v_mul_f32_e32 v129, 0x3fb8aa3b, v120
	v_mul_f32_e32 v130, 0x3fb8aa3b, v125
	v_exp_f32_e32 v129, v129
	v_exp_f32_e32 v130, v130
	v_mul_f32_e32 v131, 0x3fb8aa3b, v126
	v_mul_f32_e32 v133, 0x3fb8aa3b, v122
	v_add_f32_e32 v129, 1.0, v129
	v_rcp_f32_e32 v132, v129
	v_add_f32_e32 v129, 1.0, v130
	v_mul_f32_e32 v130, 0x3fb8aa3b, v121
	v_exp_f32_e32 v130, v130
	v_exp_f32_e32 v131, v131
	v_exp_f32_e32 v133, v133
	v_mul_f32_e32 v128, 0x3fb8aa3b, v124
	v_add_f32_e32 v136, 1.0, v130
	v_add_f32_e32 v130, 1.0, v131
	v_add_f32_e32 v131, 1.0, v133
	v_mul_f32_e32 v133, 0x3fb8aa3b, v127
	v_mul_f32_e32 v134, 0x3fb8aa3b, v123
	v_exp_f32_e32 v128, v128
	v_exp_f32_e32 v133, v133
	v_exp_f32_e32 v135, v134
	v_rcp_f32_e32 v134, v131
	v_add_f32_e32 v128, 1.0, v128
	v_add_f32_e32 v131, 1.0, v133
	v_add_f32_e32 v133, 1.0, v135
	v_rcp_f32_e32 v128, v128
	v_rcp_f32_e32 v129, v129
	v_rcp_f32_e32 v130, v130
	v_rcp_f32_e32 v131, v131
	v_rcp_f32_e32 v135, v133
	v_rcp_f32_e32 v133, v136
	s_waitcnt vmcnt(0)
	v_pk_mul_f32 v[128:129], v[128:129], v[52:53]
	v_pk_mul_f32 v[130:131], v[130:131], v[54:55]
	v_pk_mul_f32 v[134:135], v[134:135], v[46:47]
	v_pk_mul_f32 v[132:133], v[132:133], v[44:45]

.LBB0_172:
	v_or_b32_e32 v120, 16, v170
	v_ashrrev_i32_e32 v121, 31, v120
	v_lshlrev_b64 v[120:121], 13, v[120:121]
	v_lshl_add_u64 v[136:137], v[172:173], 0, v[120:121]
	v_cvt_pk_bf16_f32 v120, v128, v129
	v_cvt_pk_bf16_f32 v121, v130, v131
	v_cvt_pk_bf16_f32 v122, v132, v133
	v_cvt_pk_bf16_f32 v123, v134, v135
	s_and_b64 vcc, exec, s[8:9]
	s_mov_b64 s[24:25], -1
	global_store_dwordx4 v[136:137], v[120:123], off sc1
	s_cbranch_vccnz .LBB0_176
	v_mov_b64_e32 v[126:127], v[114:115]
	v_mov_b64_e32 v[122:123], v[118:119]
	s_and_b64 vcc, exec, s[6:7]
	v_mov_b64_e32 v[124:125], v[112:113]
	v_mov_b64_e32 v[120:121], v[116:117]
	s_cbranch_vccnz .LBB0_175
	v_mul_f32_e32 v121, 0x3fb8aa3b, v112
	v_mul_f32_e32 v122, 0x3fb8aa3b, v117
	v_exp_f32_e32 v121, v121
	v_exp_f32_e32 v122, v122
	v_mul_f32_e32 v123, 0x3fb8aa3b, v118
	v_mul_f32_e32 v125, 0x3fb8aa3b, v114
	v_add_f32_e32 v121, 1.0, v121
	v_rcp_f32_e32 v124, v121
	v_add_f32_e32 v121, 1.0, v122
	v_mul_f32_e32 v122, 0x3fb8aa3b, v113
	v_exp_f32_e32 v122, v122
	v_exp_f32_e32 v123, v123
	v_exp_f32_e32 v125, v125
	v_mul_f32_e32 v120, 0x3fb8aa3b, v116
	v_add_f32_e32 v128, 1.0, v122
	v_add_f32_e32 v122, 1.0, v123
	v_add_f32_e32 v123, 1.0, v125
	v_mul_f32_e32 v125, 0x3fb8aa3b, v119
	v_mul_f32_e32 v126, 0x3fb8aa3b, v115
	v_exp_f32_e32 v120, v120
	v_exp_f32_e32 v125, v125
	v_exp_f32_e32 v127, v126
	v_rcp_f32_e32 v126, v123
	v_add_f32_e32 v120, 1.0, v120
	v_add_f32_e32 v123, 1.0, v125
	v_add_f32_e32 v125, 1.0, v127
	v_rcp_f32_e32 v120, v120
	v_rcp_f32_e32 v121, v121
	v_rcp_f32_e32 v122, v122
	v_rcp_f32_e32 v123, v123
	v_rcp_f32_e32 v127, v125
	v_rcp_f32_e32 v125, v128
	s_waitcnt vmcnt(0)
	v_pk_mul_f32 v[120:121], v[120:121], v[28:29]
	v_pk_mul_f32 v[122:123], v[122:123], v[30:31]
	v_pk_mul_f32 v[126:127], v[126:127], v[26:27]
	v_pk_mul_f32 v[124:125], v[124:125], v[24:25]

.LBB0_178:
	v_cvt_pk_bf16_f32 v112, v120, v121
	v_cvt_pk_bf16_f32 v113, v122, v123
	v_cvt_pk_bf16_f32 v114, v124, v125
	v_cvt_pk_bf16_f32 v115, v126, v127
	s_and_b64 vcc, exec, s[8:9]
	s_mov_b64 s[24:25], -1
	global_store_dwordx4 v[136:137], v[112:115], off offset:256 sc1
	s_cbranch_vccnz .LBB0_182
	v_mov_b64_e32 v[118:119], v[106:107]
	v_mov_b64_e32 v[114:115], v[110:111]
	s_and_b64 vcc, exec, s[6:7]
	v_mov_b64_e32 v[116:117], v[104:105]
	v_mov_b64_e32 v[112:113], v[108:109]
	s_cbranch_vccnz .LBB0_181
	v_mul_f32_e32 v113, 0x3fb8aa3b, v104
	v_mul_f32_e32 v114, 0x3fb8aa3b, v109
	v_exp_f32_e32 v113, v113
	v_exp_f32_e32 v114, v114
	v_mul_f32_e32 v115, 0x3fb8aa3b, v110
	v_mul_f32_e32 v117, 0x3fb8aa3b, v106
	v_add_f32_e32 v113, 1.0, v113
	v_rcp_f32_e32 v116, v113
	v_add_f32_e32 v113, 1.0, v114
	v_mul_f32_e32 v114, 0x3fb8aa3b, v105
	v_exp_f32_e32 v114, v114
	v_exp_f32_e32 v115, v115
	v_exp_f32_e32 v117, v117
	v_mul_f32_e32 v112, 0x3fb8aa3b, v108
	v_add_f32_e32 v120, 1.0, v114
	v_add_f32_e32 v114, 1.0, v115
	v_add_f32_e32 v115, 1.0, v117
	v_mul_f32_e32 v117, 0x3fb8aa3b, v111
	v_mul_f32_e32 v118, 0x3fb8aa3b, v107
	v_exp_f32_e32 v112, v112
	v_exp_f32_e32 v117, v117
	v_exp_f32_e32 v119, v118
	v_rcp_f32_e32 v118, v115
	v_add_f32_e32 v112, 1.0, v112
	v_add_f32_e32 v115, 1.0, v117
	v_add_f32_e32 v117, 1.0, v119
	v_rcp_f32_e32 v112, v112
	v_rcp_f32_e32 v113, v113
	v_rcp_f32_e32 v114, v114
	v_rcp_f32_e32 v115, v115
	v_rcp_f32_e32 v119, v117
	v_rcp_f32_e32 v117, v120
	s_waitcnt vmcnt(0)
	v_pk_mul_f32 v[112:113], v[112:113], v[52:53]
	v_pk_mul_f32 v[114:115], v[114:115], v[54:55]
	v_pk_mul_f32 v[118:119], v[118:119], v[46:47]
	v_pk_mul_f32 v[116:117], v[116:117], v[44:45]

.LBB0_184:
	v_or_b32_e32 v104, 32, v170
	v_ashrrev_i32_e32 v105, 31, v104
	v_lshlrev_b64 v[104:105], 13, v[104:105]
	v_lshl_add_u64 v[120:121], v[172:173], 0, v[104:105]
	v_cvt_pk_bf16_f32 v104, v112, v113
	v_cvt_pk_bf16_f32 v105, v114, v115
	v_cvt_pk_bf16_f32 v106, v116, v117
	v_cvt_pk_bf16_f32 v107, v118, v119
	s_and_b64 vcc, exec, s[8:9]
	s_mov_b64 s[24:25], -1
	global_store_dwordx4 v[120:121], v[104:107], off sc1
	s_cbranch_vccnz .LBB0_188
	v_mov_b64_e32 v[110:111], v[98:99]
	v_mov_b64_e32 v[106:107], v[102:103]
	s_and_b64 vcc, exec, s[6:7]
	v_mov_b64_e32 v[108:109], v[96:97]
	v_mov_b64_e32 v[104:105], v[100:101]
	s_cbranch_vccnz .LBB0_187
	v_mul_f32_e32 v105, 0x3fb8aa3b, v96
	v_mul_f32_e32 v106, 0x3fb8aa3b, v101
	v_exp_f32_e32 v105, v105
	v_exp_f32_e32 v106, v106
	v_mul_f32_e32 v107, 0x3fb8aa3b, v102
	v_mul_f32_e32 v109, 0x3fb8aa3b, v98
	v_add_f32_e32 v105, 1.0, v105
	v_rcp_f32_e32 v108, v105
	v_add_f32_e32 v105, 1.0, v106
	v_mul_f32_e32 v106, 0x3fb8aa3b, v97
	v_exp_f32_e32 v106, v106
	v_exp_f32_e32 v107, v107
	v_exp_f32_e32 v109, v109
	v_mul_f32_e32 v104, 0x3fb8aa3b, v100
	v_add_f32_e32 v112, 1.0, v106
	v_add_f32_e32 v106, 1.0, v107
	v_add_f32_e32 v107, 1.0, v109
	v_mul_f32_e32 v109, 0x3fb8aa3b, v103
	v_mul_f32_e32 v110, 0x3fb8aa3b, v99
	v_exp_f32_e32 v104, v104
	v_exp_f32_e32 v109, v109
	v_exp_f32_e32 v111, v110
	v_rcp_f32_e32 v110, v107
	v_add_f32_e32 v104, 1.0, v104
	v_add_f32_e32 v107, 1.0, v109
	v_add_f32_e32 v109, 1.0, v111
	v_rcp_f32_e32 v104, v104
	v_rcp_f32_e32 v105, v105
	v_rcp_f32_e32 v106, v106
	v_rcp_f32_e32 v107, v107
	v_rcp_f32_e32 v111, v109
	v_rcp_f32_e32 v109, v112
	s_waitcnt vmcnt(0)
	v_pk_mul_f32 v[104:105], v[104:105], v[28:29]
	v_pk_mul_f32 v[106:107], v[106:107], v[30:31]
	v_pk_mul_f32 v[110:111], v[110:111], v[26:27]
	v_pk_mul_f32 v[108:109], v[108:109], v[24:25]

.LBB0_190:
	v_cvt_pk_bf16_f32 v96, v104, v105
	v_cvt_pk_bf16_f32 v97, v106, v107
	v_cvt_pk_bf16_f32 v98, v108, v109
	v_cvt_pk_bf16_f32 v99, v110, v111
	s_and_b64 vcc, exec, s[8:9]
	s_mov_b64 s[24:25], -1
	global_store_dwordx4 v[120:121], v[96:99], off offset:256 sc1
	s_cbranch_vccnz .LBB0_194
	v_mov_b64_e32 v[102:103], v[90:91]
	v_mov_b64_e32 v[98:99], v[94:95]
	s_and_b64 vcc, exec, s[6:7]
	v_mov_b64_e32 v[100:101], v[88:89]
	v_mov_b64_e32 v[96:97], v[92:93]
	s_cbranch_vccnz .LBB0_193
	v_mul_f32_e32 v97, 0x3fb8aa3b, v88
	v_mul_f32_e32 v98, 0x3fb8aa3b, v93
	v_exp_f32_e32 v97, v97
	v_exp_f32_e32 v98, v98
	v_mul_f32_e32 v99, 0x3fb8aa3b, v94
	v_mul_f32_e32 v101, 0x3fb8aa3b, v90
	v_add_f32_e32 v97, 1.0, v97
	v_rcp_f32_e32 v100, v97
	v_add_f32_e32 v97, 1.0, v98
	v_mul_f32_e32 v98, 0x3fb8aa3b, v89
	v_exp_f32_e32 v98, v98
	v_exp_f32_e32 v99, v99
	v_exp_f32_e32 v101, v101
	v_mul_f32_e32 v96, 0x3fb8aa3b, v92
	v_add_f32_e32 v104, 1.0, v98
	v_add_f32_e32 v98, 1.0, v99
	v_add_f32_e32 v99, 1.0, v101
	v_mul_f32_e32 v101, 0x3fb8aa3b, v95
	v_mul_f32_e32 v102, 0x3fb8aa3b, v91
	v_exp_f32_e32 v96, v96
	v_exp_f32_e32 v101, v101
	v_exp_f32_e32 v103, v102
	v_rcp_f32_e32 v102, v99
	v_add_f32_e32 v96, 1.0, v96
	v_add_f32_e32 v99, 1.0, v101
	v_add_f32_e32 v101, 1.0, v103
	v_rcp_f32_e32 v96, v96
	v_rcp_f32_e32 v97, v97
	v_rcp_f32_e32 v98, v98
	v_rcp_f32_e32 v99, v99
	v_rcp_f32_e32 v103, v101
	v_rcp_f32_e32 v101, v104
	s_waitcnt vmcnt(0)
	v_pk_mul_f32 v[96:97], v[96:97], v[52:53]
	v_pk_mul_f32 v[98:99], v[98:99], v[54:55]
	v_pk_mul_f32 v[102:103], v[102:103], v[46:47]
	v_pk_mul_f32 v[100:101], v[100:101], v[44:45]

.LBB0_196:
	v_or_b32_e32 v88, 48, v170
	v_ashrrev_i32_e32 v89, 31, v88
	v_lshlrev_b64 v[88:89], 13, v[88:89]
	v_lshl_add_u64 v[104:105], v[172:173], 0, v[88:89]
	v_cvt_pk_bf16_f32 v88, v96, v97
	v_cvt_pk_bf16_f32 v89, v98, v99
	v_cvt_pk_bf16_f32 v90, v100, v101
	v_cvt_pk_bf16_f32 v91, v102, v103
	s_and_b64 vcc, exec, s[8:9]
	s_mov_b64 s[24:25], -1
	global_store_dwordx4 v[104:105], v[88:91], off sc1
	s_cbranch_vccnz .LBB0_200
	v_mov_b64_e32 v[94:95], v[82:83]
	v_mov_b64_e32 v[90:91], v[86:87]
	s_and_b64 vcc, exec, s[6:7]
	v_mov_b64_e32 v[92:93], v[80:81]
	v_mov_b64_e32 v[88:89], v[84:85]
	s_cbranch_vccnz .LBB0_199
	v_mul_f32_e32 v89, 0x3fb8aa3b, v80
	v_mul_f32_e32 v90, 0x3fb8aa3b, v85
	v_exp_f32_e32 v89, v89
	v_exp_f32_e32 v90, v90
	v_mul_f32_e32 v91, 0x3fb8aa3b, v86
	v_mul_f32_e32 v93, 0x3fb8aa3b, v82
	v_add_f32_e32 v89, 1.0, v89
	v_rcp_f32_e32 v92, v89
	v_add_f32_e32 v89, 1.0, v90
	v_mul_f32_e32 v90, 0x3fb8aa3b, v81
	v_exp_f32_e32 v90, v90
	v_exp_f32_e32 v91, v91
	v_exp_f32_e32 v93, v93
	v_mul_f32_e32 v88, 0x3fb8aa3b, v84
	v_add_f32_e32 v96, 1.0, v90
	v_add_f32_e32 v90, 1.0, v91
	v_add_f32_e32 v91, 1.0, v93
	v_mul_f32_e32 v93, 0x3fb8aa3b, v87
	v_mul_f32_e32 v94, 0x3fb8aa3b, v83
	v_exp_f32_e32 v88, v88
	v_exp_f32_e32 v93, v93
	v_exp_f32_e32 v95, v94
	v_rcp_f32_e32 v94, v91
	v_add_f32_e32 v88, 1.0, v88
	v_add_f32_e32 v91, 1.0, v93
	v_add_f32_e32 v93, 1.0, v95
	v_rcp_f32_e32 v88, v88
	v_rcp_f32_e32 v89, v89
	v_rcp_f32_e32 v90, v90
	v_rcp_f32_e32 v91, v91
	v_rcp_f32_e32 v95, v93
	v_rcp_f32_e32 v93, v96
	s_waitcnt vmcnt(0)
	v_pk_mul_f32 v[88:89], v[88:89], v[28:29]
	v_pk_mul_f32 v[90:91], v[90:91], v[30:31]
	v_pk_mul_f32 v[94:95], v[94:95], v[26:27]
	v_pk_mul_f32 v[92:93], v[92:93], v[24:25]

.LBB0_202:
	v_cvt_pk_bf16_f32 v80, v88, v89
	v_cvt_pk_bf16_f32 v81, v90, v91
	v_cvt_pk_bf16_f32 v82, v92, v93
	v_cvt_pk_bf16_f32 v83, v94, v95
	s_and_b64 vcc, exec, s[8:9]
	s_mov_b64 s[24:25], -1
	global_store_dwordx4 v[104:105], v[80:83], off offset:256 sc1
	s_cbranch_vccnz .LBB0_206
	v_mov_b64_e32 v[86:87], v[74:75]
	v_mov_b64_e32 v[82:83], v[78:79]
	s_and_b64 vcc, exec, s[6:7]
	v_mov_b64_e32 v[84:85], v[72:73]
	v_mov_b64_e32 v[80:81], v[76:77]
	s_cbranch_vccnz .LBB0_205
	v_mul_f32_e32 v81, 0x3fb8aa3b, v72
	v_mul_f32_e32 v82, 0x3fb8aa3b, v77
	v_exp_f32_e32 v81, v81
	v_exp_f32_e32 v82, v82
	v_mul_f32_e32 v83, 0x3fb8aa3b, v78
	v_mul_f32_e32 v85, 0x3fb8aa3b, v74
	v_add_f32_e32 v81, 1.0, v81
	v_rcp_f32_e32 v84, v81
	v_add_f32_e32 v81, 1.0, v82
	v_mul_f32_e32 v82, 0x3fb8aa3b, v73
	v_exp_f32_e32 v82, v82
	v_exp_f32_e32 v83, v83
	v_exp_f32_e32 v85, v85
	v_mul_f32_e32 v80, 0x3fb8aa3b, v76
	v_add_f32_e32 v88, 1.0, v82
	v_add_f32_e32 v82, 1.0, v83
	v_add_f32_e32 v83, 1.0, v85
	v_mul_f32_e32 v85, 0x3fb8aa3b, v79
	v_mul_f32_e32 v86, 0x3fb8aa3b, v75
	v_exp_f32_e32 v80, v80
	v_exp_f32_e32 v85, v85
	v_exp_f32_e32 v87, v86
	v_rcp_f32_e32 v86, v83
	v_add_f32_e32 v80, 1.0, v80
	v_add_f32_e32 v83, 1.0, v85
	v_add_f32_e32 v85, 1.0, v87
	v_rcp_f32_e32 v80, v80
	v_rcp_f32_e32 v81, v81
	v_rcp_f32_e32 v82, v82
	v_rcp_f32_e32 v83, v83
	v_rcp_f32_e32 v87, v85
	v_rcp_f32_e32 v85, v88
	s_waitcnt vmcnt(0)
	v_pk_mul_f32 v[80:81], v[80:81], v[52:53]
	v_pk_mul_f32 v[82:83], v[82:83], v[54:55]
	v_pk_mul_f32 v[86:87], v[86:87], v[46:47]
	v_pk_mul_f32 v[84:85], v[84:85], v[44:45]

.LBB0_208:
	v_lshlrev_b64 v[72:73], 13, v[170:171]
	v_lshl_add_u64 v[88:89], v[172:173], 0, v[72:73]
	v_add_co_u32_e32 v76, vcc, 0x100000, v88
	v_cvt_pk_bf16_f32 v72, v80, v81
	s_nop 0
	v_addc_co_u32_e32 v77, vcc, 0, v89, vcc
	v_cvt_pk_bf16_f32 v73, v82, v83
	v_cvt_pk_bf16_f32 v74, v84, v85
	v_cvt_pk_bf16_f32 v75, v86, v87
	s_and_b64 vcc, exec, s[8:9]
	s_mov_b64 s[24:25], -1
	global_store_dwordx4 v[76:77], v[72:75], off sc1
	s_cbranch_vccnz .LBB0_212
	v_mov_b64_e32 v[78:79], v[66:67]
	v_mov_b64_e32 v[74:75], v[70:71]
	s_and_b64 vcc, exec, s[6:7]
	v_mov_b64_e32 v[76:77], v[64:65]
	v_mov_b64_e32 v[72:73], v[68:69]
	s_cbranch_vccnz .LBB0_211
	v_mul_f32_e32 v73, 0x3fb8aa3b, v64
	v_mul_f32_e32 v74, 0x3fb8aa3b, v69
	v_exp_f32_e32 v73, v73
	v_exp_f32_e32 v74, v74
	v_mul_f32_e32 v75, 0x3fb8aa3b, v70
	v_mul_f32_e32 v77, 0x3fb8aa3b, v66
	v_add_f32_e32 v73, 1.0, v73
	v_rcp_f32_e32 v76, v73
	v_add_f32_e32 v73, 1.0, v74
	v_mul_f32_e32 v74, 0x3fb8aa3b, v65
	v_exp_f32_e32 v74, v74
	v_exp_f32_e32 v75, v75
	v_exp_f32_e32 v77, v77
	v_mul_f32_e32 v72, 0x3fb8aa3b, v68
	v_add_f32_e32 v80, 1.0, v74
	v_add_f32_e32 v74, 1.0, v75
	v_add_f32_e32 v75, 1.0, v77
	v_mul_f32_e32 v77, 0x3fb8aa3b, v71
	v_mul_f32_e32 v78, 0x3fb8aa3b, v67
	v_exp_f32_e32 v72, v72
	v_exp_f32_e32 v77, v77
	v_exp_f32_e32 v79, v78
	v_rcp_f32_e32 v78, v75
	v_add_f32_e32 v72, 1.0, v72
	v_add_f32_e32 v75, 1.0, v77
	v_add_f32_e32 v77, 1.0, v79
	v_rcp_f32_e32 v72, v72
	v_rcp_f32_e32 v73, v73
	v_rcp_f32_e32 v74, v74
	v_rcp_f32_e32 v75, v75
	v_rcp_f32_e32 v79, v77
	v_rcp_f32_e32 v77, v80
	s_waitcnt vmcnt(0)
	v_pk_mul_f32 v[72:73], v[72:73], v[28:29]
	v_pk_mul_f32 v[74:75], v[74:75], v[30:31]
	v_pk_mul_f32 v[78:79], v[78:79], v[26:27]
	v_pk_mul_f32 v[76:77], v[76:77], v[24:25]

.LBB0_214:
	s_mov_b64 s[24:25], 0x100000
	v_lshl_add_u64 v[68:69], v[88:89], 0, s[24:25]
	v_cvt_pk_bf16_f32 v64, v72, v73
	v_cvt_pk_bf16_f32 v65, v74, v75
	v_cvt_pk_bf16_f32 v66, v76, v77
	v_cvt_pk_bf16_f32 v67, v78, v79
	s_and_b64 vcc, exec, s[8:9]
	s_mov_b64 s[24:25], -1
	global_store_dwordx4 v[68:69], v[64:67], off offset:256 sc1
	s_cbranch_vccnz .LBB0_218
	v_mov_b64_e32 v[70:71], v[58:59]
	v_mov_b64_e32 v[66:67], v[62:63]
	s_and_b64 vcc, exec, s[6:7]
	v_mov_b64_e32 v[68:69], v[56:57]
	v_mov_b64_e32 v[64:65], v[60:61]
	s_cbranch_vccnz .LBB0_217
	v_mul_f32_e32 v65, 0x3fb8aa3b, v56
	v_mul_f32_e32 v66, 0x3fb8aa3b, v61
	v_exp_f32_e32 v65, v65
	v_exp_f32_e32 v66, v66
	v_mul_f32_e32 v67, 0x3fb8aa3b, v62
	v_mul_f32_e32 v69, 0x3fb8aa3b, v58
	v_add_f32_e32 v65, 1.0, v65
	v_rcp_f32_e32 v68, v65
	v_add_f32_e32 v65, 1.0, v66
	v_mul_f32_e32 v66, 0x3fb8aa3b, v57
	v_exp_f32_e32 v66, v66
	v_exp_f32_e32 v67, v67
	v_exp_f32_e32 v69, v69
	v_mul_f32_e32 v64, 0x3fb8aa3b, v60
	v_add_f32_e32 v72, 1.0, v66
	v_add_f32_e32 v66, 1.0, v67
	v_add_f32_e32 v67, 1.0, v69
	v_mul_f32_e32 v69, 0x3fb8aa3b, v63
	v_mul_f32_e32 v70, 0x3fb8aa3b, v59
	v_exp_f32_e32 v64, v64
	v_exp_f32_e32 v69, v69
	v_exp_f32_e32 v71, v70
	v_rcp_f32_e32 v70, v67
	v_add_f32_e32 v64, 1.0, v64
	v_add_f32_e32 v67, 1.0, v69
	v_add_f32_e32 v69, 1.0, v71
	v_rcp_f32_e32 v64, v64
	v_rcp_f32_e32 v65, v65
	v_rcp_f32_e32 v66, v66
	v_rcp_f32_e32 v67, v67
	v_rcp_f32_e32 v71, v69
	v_rcp_f32_e32 v69, v72
	s_waitcnt vmcnt(0)
	v_pk_mul_f32 v[64:65], v[64:65], v[52:53]
	v_pk_mul_f32 v[66:67], v[66:67], v[54:55]
	v_pk_mul_f32 v[70:71], v[70:71], v[46:47]
	v_pk_mul_f32 v[68:69], v[68:69], v[44:45]

.LBB0_220:
	v_lshlrev_b64 v[56:57], 13, v[170:171]
	v_lshl_add_u64 v[72:73], v[172:173], 0, v[56:57]
	v_add_co_u32_e32 v60, vcc, 0x120000, v72
	v_cvt_pk_bf16_f32 v56, v64, v65
	s_nop 0
	v_addc_co_u32_e32 v61, vcc, 0, v73, vcc
	v_cvt_pk_bf16_f32 v57, v66, v67
	v_cvt_pk_bf16_f32 v58, v68, v69
	v_cvt_pk_bf16_f32 v59, v70, v71
	s_and_b64 vcc, exec, s[8:9]
	s_mov_b64 s[24:25], -1
	global_store_dwordx4 v[60:61], v[56:59], off sc1
	s_cbranch_vccnz .LBB0_224
	v_mov_b64_e32 v[62:63], v[42:43]
	v_mov_b64_e32 v[58:59], v[50:51]
	s_and_b64 vcc, exec, s[6:7]
	v_mov_b64_e32 v[60:61], v[40:41]
	v_mov_b64_e32 v[56:57], v[48:49]
	s_cbranch_vccnz .LBB0_223
	v_mul_f32_e32 v57, 0x3fb8aa3b, v40
	v_mul_f32_e32 v58, 0x3fb8aa3b, v49
	v_exp_f32_e32 v57, v57
	v_exp_f32_e32 v58, v58
	v_mul_f32_e32 v59, 0x3fb8aa3b, v50
	v_mul_f32_e32 v61, 0x3fb8aa3b, v42
	v_add_f32_e32 v57, 1.0, v57
	v_rcp_f32_e32 v60, v57
	v_add_f32_e32 v57, 1.0, v58
	v_mul_f32_e32 v58, 0x3fb8aa3b, v41
	v_exp_f32_e32 v58, v58
	v_exp_f32_e32 v59, v59
	v_exp_f32_e32 v61, v61
	v_mul_f32_e32 v56, 0x3fb8aa3b, v48
	v_add_f32_e32 v64, 1.0, v58
	v_add_f32_e32 v58, 1.0, v59
	v_add_f32_e32 v59, 1.0, v61
	v_mul_f32_e32 v61, 0x3fb8aa3b, v51
	v_mul_f32_e32 v62, 0x3fb8aa3b, v43
	v_exp_f32_e32 v56, v56
	v_exp_f32_e32 v61, v61
	v_exp_f32_e32 v63, v62
	v_rcp_f32_e32 v62, v59
	v_add_f32_e32 v56, 1.0, v56
	v_add_f32_e32 v59, 1.0, v61
	v_add_f32_e32 v61, 1.0, v63
	v_rcp_f32_e32 v56, v56
	v_rcp_f32_e32 v57, v57
	v_rcp_f32_e32 v58, v58
	v_rcp_f32_e32 v59, v59
	v_rcp_f32_e32 v63, v61
	v_rcp_f32_e32 v61, v64
	s_waitcnt vmcnt(0)
	v_pk_mul_f32 v[56:57], v[56:57], v[28:29]
	v_pk_mul_f32 v[58:59], v[58:59], v[30:31]
	v_pk_mul_f32 v[62:63], v[62:63], v[26:27]
	v_pk_mul_f32 v[60:61], v[60:61], v[24:25]

.LBB0_226:
	s_mov_b64 s[24:25], 0x120000
	v_lshl_add_u64 v[48:49], v[72:73], 0, s[24:25]
	v_cvt_pk_bf16_f32 v40, v56, v57
	v_cvt_pk_bf16_f32 v41, v58, v59
	v_cvt_pk_bf16_f32 v42, v60, v61
	v_cvt_pk_bf16_f32 v43, v62, v63
	s_and_b64 vcc, exec, s[8:9]
	s_mov_b64 s[24:25], -1
	global_store_dwordx4 v[48:49], v[40:43], off offset:256 sc1
	s_cbranch_vccnz .LBB0_230
	v_mov_b64_e32 v[50:51], v[34:35]
	v_mov_b64_e32 v[42:43], v[38:39]
	s_and_b64 vcc, exec, s[6:7]
	v_mov_b64_e32 v[48:49], v[32:33]
	v_mov_b64_e32 v[40:41], v[36:37]
	s_cbranch_vccnz .LBB0_229
	v_mul_f32_e32 v41, 0x3fb8aa3b, v32
	v_mul_f32_e32 v42, 0x3fb8aa3b, v37
	v_exp_f32_e32 v41, v41
	v_exp_f32_e32 v42, v42
	v_mul_f32_e32 v43, 0x3fb8aa3b, v38
	v_mul_f32_e32 v49, 0x3fb8aa3b, v34
	v_add_f32_e32 v41, 1.0, v41
	v_rcp_f32_e32 v48, v41
	v_add_f32_e32 v41, 1.0, v42
	v_mul_f32_e32 v42, 0x3fb8aa3b, v33
	v_exp_f32_e32 v42, v42
	v_exp_f32_e32 v43, v43
	v_exp_f32_e32 v49, v49
	v_mul_f32_e32 v40, 0x3fb8aa3b, v36
	v_add_f32_e32 v56, 1.0, v42
	v_add_f32_e32 v42, 1.0, v43
	v_add_f32_e32 v43, 1.0, v49
	v_mul_f32_e32 v49, 0x3fb8aa3b, v39
	v_mul_f32_e32 v50, 0x3fb8aa3b, v35
	v_exp_f32_e32 v40, v40
	v_exp_f32_e32 v49, v49
	v_exp_f32_e32 v51, v50
	v_rcp_f32_e32 v50, v43
	v_add_f32_e32 v40, 1.0, v40
	v_add_f32_e32 v43, 1.0, v49
	v_add_f32_e32 v49, 1.0, v51
	v_rcp_f32_e32 v40, v40
	v_rcp_f32_e32 v41, v41
	v_rcp_f32_e32 v42, v42
	v_rcp_f32_e32 v43, v43
	v_rcp_f32_e32 v51, v49
	v_rcp_f32_e32 v49, v56
	s_waitcnt vmcnt(0)
	v_pk_mul_f32 v[40:41], v[40:41], v[52:53]
	v_pk_mul_f32 v[42:43], v[42:43], v[54:55]
	v_pk_mul_f32 v[50:51], v[50:51], v[46:47]
	v_pk_mul_f32 v[48:49], v[48:49], v[44:45]

.LBB0_232:
	v_lshlrev_b64 v[32:33], 13, v[170:171]
	v_lshl_add_u64 v[56:57], v[172:173], 0, v[32:33]
	v_add_co_u32_e32 v36, vcc, 0x140000, v56
	v_cvt_pk_bf16_f32 v32, v40, v41
	s_nop 0
	v_addc_co_u32_e32 v37, vcc, 0, v57, vcc
	v_cvt_pk_bf16_f32 v33, v42, v43
	v_cvt_pk_bf16_f32 v34, v48, v49
	v_cvt_pk_bf16_f32 v35, v50, v51
	s_and_b64 vcc, exec, s[8:9]
	s_mov_b64 s[24:25], -1
	global_store_dwordx4 v[36:37], v[32:35], off sc1
	s_cbranch_vccnz .LBB0_236
	v_mov_b64_e32 v[38:39], v[18:19]
	v_mov_b64_e32 v[34:35], v[22:23]
	s_and_b64 vcc, exec, s[6:7]
	v_mov_b64_e32 v[36:37], v[16:17]
	v_mov_b64_e32 v[32:33], v[20:21]
	s_cbranch_vccnz .LBB0_235
	v_mul_f32_e32 v33, 0x3fb8aa3b, v16
	v_mul_f32_e32 v34, 0x3fb8aa3b, v21
	v_exp_f32_e32 v33, v33
	v_exp_f32_e32 v34, v34
	v_mul_f32_e32 v35, 0x3fb8aa3b, v22
	v_mul_f32_e32 v37, 0x3fb8aa3b, v18
	v_add_f32_e32 v33, 1.0, v33
	v_rcp_f32_e32 v36, v33
	v_add_f32_e32 v33, 1.0, v34
	v_mul_f32_e32 v34, 0x3fb8aa3b, v17
	v_exp_f32_e32 v34, v34
	v_exp_f32_e32 v35, v35
	v_exp_f32_e32 v37, v37
	v_mul_f32_e32 v32, 0x3fb8aa3b, v20
	v_add_f32_e32 v40, 1.0, v34
	v_add_f32_e32 v34, 1.0, v35
	v_add_f32_e32 v35, 1.0, v37
	v_mul_f32_e32 v37, 0x3fb8aa3b, v23
	v_mul_f32_e32 v38, 0x3fb8aa3b, v19
	v_exp_f32_e32 v32, v32
	v_exp_f32_e32 v37, v37
	v_exp_f32_e32 v39, v38
	v_rcp_f32_e32 v38, v35
	v_add_f32_e32 v32, 1.0, v32
	v_add_f32_e32 v35, 1.0, v37
	v_add_f32_e32 v37, 1.0, v39
	v_rcp_f32_e32 v32, v32
	v_rcp_f32_e32 v33, v33
	v_rcp_f32_e32 v34, v34
	v_rcp_f32_e32 v35, v35
	v_rcp_f32_e32 v39, v37
	v_rcp_f32_e32 v37, v40
	s_waitcnt vmcnt(0)
	v_pk_mul_f32 v[32:33], v[32:33], v[28:29]
	v_pk_mul_f32 v[34:35], v[34:35], v[30:31]
	v_pk_mul_f32 v[38:39], v[38:39], v[26:27]
	v_pk_mul_f32 v[36:37], v[36:37], v[24:25]

.LBB0_238:
	s_mov_b64 s[24:25], 0x140000
	v_lshl_add_u64 v[20:21], v[56:57], 0, s[24:25]
	v_cvt_pk_bf16_f32 v16, v32, v33
	v_cvt_pk_bf16_f32 v17, v34, v35
	v_cvt_pk_bf16_f32 v18, v36, v37
	v_cvt_pk_bf16_f32 v19, v38, v39
	s_and_b64 vcc, exec, s[8:9]
	s_mov_b64 s[24:25], -1
	global_store_dwordx4 v[20:21], v[16:19], off offset:256 sc1
	s_cbranch_vccnz .LBB0_242
	v_mov_b64_e32 v[22:23], v[10:11]
	v_mov_b64_e32 v[18:19], v[14:15]
	s_and_b64 vcc, exec, s[6:7]
	v_mov_b64_e32 v[20:21], v[8:9]
	v_mov_b64_e32 v[16:17], v[12:13]
	s_cbranch_vccnz .LBB0_241
	v_mul_f32_e32 v17, 0x3fb8aa3b, v8
	v_mul_f32_e32 v18, 0x3fb8aa3b, v9
	v_mul_f32_e32 v19, 0x3fb8aa3b, v10
	v_exp_f32_e32 v17, v17
	v_exp_f32_e32 v18, v18
	v_exp_f32_e32 v19, v19
	v_mul_f32_e32 v16, 0x3fb8aa3b, v12
	v_add_f32_e32 v17, 1.0, v17
	v_add_f32_e32 v18, 1.0, v18
	v_add_f32_e32 v19, 1.0, v19
	v_rcp_f32_e32 v20, v17
	v_mul_f32_e32 v17, 0x3fb8aa3b, v13
	v_rcp_f32_e32 v21, v18
	v_mul_f32_e32 v18, 0x3fb8aa3b, v14
	v_rcp_f32_e32 v22, v19
	v_mul_f32_e32 v19, 0x3fb8aa3b, v15
	v_mul_f32_e32 v23, 0x3fb8aa3b, v11
	v_exp_f32_e32 v16, v16
	v_exp_f32_e32 v17, v17
	v_exp_f32_e32 v18, v18
	v_exp_f32_e32 v19, v19
	v_exp_f32_e32 v23, v23
	v_add_f32_e32 v16, 1.0, v16
	v_add_f32_e32 v17, 1.0, v17
	v_add_f32_e32 v18, 1.0, v18
	v_add_f32_e32 v19, 1.0, v19
	v_add_f32_e32 v23, 1.0, v23
	v_rcp_f32_e32 v16, v16
	v_rcp_f32_e32 v17, v17
	v_rcp_f32_e32 v18, v18
	v_rcp_f32_e32 v19, v19
	v_rcp_f32_e32 v23, v23
	s_waitcnt vmcnt(0)
	v_pk_mul_f32 v[16:17], v[16:17], v[52:53]
	v_pk_mul_f32 v[20:21], v[20:21], v[44:45]
	v_pk_mul_f32 v[18:19], v[18:19], v[54:55]
	v_pk_mul_f32 v[22:23], v[22:23], v[46:47]

.LBB0_244:
	v_lshlrev_b64 v[8:9], 13, v[170:171]
	v_lshl_add_u64 v[32:33], v[172:173], 0, v[8:9]
	v_add_co_u32_e32 v12, vcc, 0x160000, v32
	v_cvt_pk_bf16_f32 v8, v16, v17
	s_nop 0
	v_addc_co_u32_e32 v13, vcc, 0, v33, vcc
	v_cvt_pk_bf16_f32 v9, v18, v19
	v_cvt_pk_bf16_f32 v10, v20, v21
	v_cvt_pk_bf16_f32 v11, v22, v23
	s_and_b64 vcc, exec, s[8:9]
	s_mov_b64 s[8:9], -1
	global_store_dwordx4 v[12:13], v[8:11], off sc1
	s_cbranch_vccnz .LBB0_248
	v_mov_b64_e32 v[14:15], v[2:3]
	v_mov_b64_e32 v[10:11], v[6:7]
	s_and_b64 vcc, exec, s[6:7]
	v_mov_b64_e32 v[12:13], v[0:1]
	v_mov_b64_e32 v[8:9], v[4:5]
	s_cbranch_vccnz .LBB0_247
	v_mul_f32_e32 v9, 0x3fb8aa3b, v0
	v_mul_f32_e32 v10, 0x3fb8aa3b, v1
	v_mul_f32_e32 v11, 0x3fb8aa3b, v2
	v_exp_f32_e32 v9, v9
	v_exp_f32_e32 v10, v10
	v_exp_f32_e32 v11, v11
	v_mul_f32_e32 v8, 0x3fb8aa3b, v4
	v_add_f32_e32 v9, 1.0, v9
	v_add_f32_e32 v10, 1.0, v10
	v_add_f32_e32 v11, 1.0, v11
	v_rcp_f32_e32 v12, v9
	v_mul_f32_e32 v9, 0x3fb8aa3b, v5
	v_rcp_f32_e32 v13, v10
	v_mul_f32_e32 v10, 0x3fb8aa3b, v6
	v_rcp_f32_e32 v14, v11
	v_mul_f32_e32 v11, 0x3fb8aa3b, v7
	v_mul_f32_e32 v15, 0x3fb8aa3b, v3
	v_exp_f32_e32 v8, v8
	v_exp_f32_e32 v9, v9
	v_exp_f32_e32 v10, v10
	v_exp_f32_e32 v11, v11
	v_exp_f32_e32 v15, v15
	v_add_f32_e32 v8, 1.0, v8
	v_add_f32_e32 v9, 1.0, v9
	v_add_f32_e32 v10, 1.0, v10
	v_add_f32_e32 v11, 1.0, v11
	v_add_f32_e32 v15, 1.0, v15
	v_rcp_f32_e32 v8, v8
	v_rcp_f32_e32 v9, v9
	v_rcp_f32_e32 v10, v10
	v_rcp_f32_e32 v11, v11
	v_rcp_f32_e32 v15, v15
	s_waitcnt vmcnt(0)
	v_pk_mul_f32 v[8:9], v[8:9], v[28:29]
	v_pk_mul_f32 v[12:13], v[12:13], v[24:25]
	v_pk_mul_f32 v[10:11], v[10:11], v[30:31]
	v_pk_mul_f32 v[14:15], v[14:15], v[26:27]

.LBB0_250:
	s_mov_b64 s[6:7], 0x160000
	v_lshl_add_u64 v[4:5], v[32:33], 0, s[6:7]
	v_cvt_pk_bf16_f32 v0, v8, v9
	v_cvt_pk_bf16_f32 v1, v10, v11
	v_cvt_pk_bf16_f32 v2, v12, v13
	v_cvt_pk_bf16_f32 v3, v14, v15
	s_and_b64 vcc, exec, s[4:5]
	s_mov_b64 s[4:5], -1
	global_store_dwordx4 v[4:5], v[0:3], off offset:256 sc1
	s_cbranch_vccnz .LBB0_131
	s_andn2_b64 vcc, exec, s[12:13]
	s_cbranch_vccnz .LBB0_130
	s_barrier
	s_branch .LBB0_130

.Lovl_after_p1:
	s_waitcnt vmcnt(0)
	v_mov_b32_e32 v253, 0x3c00
	v_readfirstlane_b32 s99, v208
	s_lshr_b32 s99, s99, 6
	s_cmp_lg_u32 s99, 0
	s_cbranch_scc1 .Lovl_c4_nosig
	buffer_wbl2 sc1
	s_waitcnt vmcnt(0)
	v_mov_b32_e32 v254, 1
	s_mov_b64 s[100:101], exec
	s_mov_b64 exec, 1
	global_atomic_add v253, v254, s[74:75]
	s_mov_b64 exec, s[100:101]
.Lovl_c4_nosig:
	v_readfirstlane_b32 s99, v208
	s_lshr_b32 s99, s99, 6
	s_cmp_lg_u32 s99, 0
	s_cbranch_scc1 .Lspin_join_c4
	s_mov_b32 s99, 0
.Lspin_c4:
	global_load_dword v254, v253, s[74:75] sc1
	s_waitcnt vmcnt(0)
	v_readfirstlane_b32 s100, v254
	s_cmp_ge_u32 s100, 0xc0
	s_cbranch_scc1 .Lspin_done_c4
	s_sleep 24
	s_add_u32 s99, s99, 1
	s_cmp_lt_u32 s99, 0x2000
	s_cbranch_scc1 .Lspin_c4

.Lspin_join_c4:
.Lovl_p2_entry:
	s_cmpk_gt_i32 s3, 0x3f
	s_waitcnt lgkmcnt(0)
	s_barrier
	s_cbranch_scc0 .LBB0_351
	v_mov_b32_e32 v4, v208
	s_lshl_b32 s1, s3, 3
	v_readfirstlane_b32 s0, v4
	s_ashr_i32 s0, s0, 6
	s_add_i32 s1, s1, s0
	s_add_i32 s18, s1, 0x600
	s_cmpk_gt_i32 s18, 0x31ff
	s_cbranch_scc1 .LBB0_351
	s_lshl_b32 s0, s0, 14
	v_bfe_u32 v102, v4, 5, 1
	v_lshlrev_b32_e32 v0, 2, v4
	v_bfe_u32 v104, v4, 3, 3
	v_lshlrev_b32_e32 v4, 3, v4
	s_add_i32 s19, s76, 0xfffffe00
	s_add_i32 s0, s0, 0
	v_mov_b32_e32 v1, 0
	v_and_b32_e32 v4, 56, v4
	v_readlane_b32 s4, v252, 5
	v_and_b32_e32 v0, 0x7c, v0
	v_mul_u32_u24_e32 v5, 0x84, v102
	v_lshlrev_b32_e32 v34, 1, v4
	v_mov_b32_e32 v35, v1
	v_readlane_b32 s5, v252, 6
	s_cmp_lg_u64 s[56:57], 0
	v_add3_u32 v103, s0, v0, v5
	v_mul_u32_u24_e32 v6, 0x84, v4
	v_lshl_add_u64 v[4:5], s[4:5], 0, v[34:35]
	s_cselect_b64 s[4:5], -1, 0
	s_add_u32 s6, s46, 0x4000
	v_readlane_b32 s8, v252, 9
	s_addc_u32 s7, s47, 0
	v_lshl_add_u64 v[12:13], s[70:71], 0, v[0:1]
	s_mov_b64 s[12:13], 0x1000000
	v_readlane_b32 s9, v252, 10
	v_lshl_add_u64 v[20:21], s[68:69], 0, v[0:1]
	v_lshl_add_u64 v[14:15], v[12:13], 0, s[12:13]
	v_lshl_add_u64 v[16:17], s[8:9], 0, v[34:35]
	s_add_u32 s8, s46, 0x6000
	v_lshl_add_u64 v[22:23], v[20:21], 0, s[12:13]
	v_readlane_b32 s12, v252, 7
	s_addc_u32 s9, s47, 0
	v_readlane_b32 s13, v252, 8
	v_lshlrev_b32_e32 v7, 2, v104
	v_add3_u32 v105, s0, v6, v7
	v_lshl_add_u64 v[24:25], s[12:13], 0, v[34:35]
	s_add_u32 s12, s46, 0x2000
	s_addc_u32 s13, s47, 0
	s_cmp_lg_u64 s[46:47], 0
	s_cselect_b64 s[14:15], -1, 0
	s_lshl_b32 s0, s18, 1
	s_mov_b32 s1, 0
	v_lshl_add_u64 v[2:3], s[66:67], 0, v[0:1]
	v_or_b32_e32 v106, 8, v104
	v_or_b32_e32 v107, 16, v104
	v_or_b32_e32 v108, 24, v104
	v_lshl_add_u64 v[6:7], s[58:59], 0, v[0:1]
	v_lshl_add_u64 v[8:9], s[88:89], 0, v[34:35]
	v_lshl_add_u64 v[10:11], s[60:61], 0, v[0:1]
	v_lshl_add_u64 v[18:19], s[30:31], 0, v[34:35]
	v_lshl_add_u64 v[26:27], s[34:35], 0, v[34:35]
	v_lshl_add_u64 v[28:29], s[54:55], 0, v[0:1]
	v_lshl_add_u64 v[30:31], s[94:95], 0, v[34:35]
	v_lshl_add_u64 v[32:33], s[48:49], 0, v[0:1]
	v_lshl_add_u64 v[34:35], s[10:11], 0, v[34:35]
	s_lshl_b32 s20, s18, 5
	s_lshl_b32 s21, s19, 5
	s_mov_b32 s22, 0x1a000
	s_add_i32 s23, s0, 0x1a000
	s_lshl_b32 s24, s19, 1
	v_add_u32_e32 v109, 0x400, v103
	v_add_u32_e32 v110, 0x800, v103
	v_add_u32_e32 v111, 0xc00, v103
	v_add_u32_e32 v112, 0x1000, v103
	v_add_u32_e32 v113, 0x1400, v103
	v_add_u32_e32 v114, 0x1800, v103
	v_add_u32_e32 v115, 0x1c00, v103
	s_branch .LBB0_311

.LBB0_469:
	s_and_b64 vcc, exec, s[0:1]
	s_cbranch_vccz .LBB0_354
	v_mov_b32_e32 v253, 0x3800
	v_readfirstlane_b32 s99, v208
	s_lshr_b32 s99, s99, 6
	s_cmp_lg_u32 s99, 0
	s_cbranch_scc1 .Lspin_join_g0
	s_mov_b32 s99, 0

.Lspin_join_g0:
	s_barrier
	v_mov_b32_e32 v36, v208
	s_lshl_b32 s0, s81, 1
	v_readfirstlane_b32 s6, v36
	s_ashr_i32 s7, s6, 6
	s_and_b32 s86, s0, 0x700
	s_lshl_b32 s0, s7, 5
	s_add_i32 s8, 0, 0x13c00
	v_bfe_u32 v38, v36, 4, 2
	s_add_i32 s0, s8, s0
	v_lshl_add_u32 v39, v38, 3, s0
	s_mov_b32 s0, s87
	s_mov_b32 s1, s87
	s_ashr_i32 s36, s70, 3
	v_and_b32_e32 v107, 15, v36
	s_mul_i32 s4, s7, 0x900
	v_mov_b64_e32 v[2:3], s[0:1]
	s_and_b32 s14, s7, 1
	s_lshl_b32 s0, s70, 7
	s_ashr_i32 s37, s36, 31
	v_mad_u32_u24 v0, v107, s83, v39
	s_and_b32 s0, s0, 0x380
	v_lshl_or_b32 v41, s14, 6, v107
	s_add_i32 s1, s4, 0
	s_lshl_b64 s[30:31], s[36:37], 13
	s_barrier
	ds_write_b64 v0, v[2:3]
	ds_write_b64 v0, v[2:3] offset:4352
	ds_write_b64 v0, v[2:3] offset:8704
	ds_write_b64 v0, v[2:3] offset:13056
	ds_write_b64 v0, v[2:3] offset:17408
	ds_write_b64 v0, v[2:3] offset:21760
	ds_write_b64 v0, v[2:3] offset:26112
	ds_write_b64 v0, v[2:3] offset:30464
	v_or_b32_e32 v0, s0, v41
	s_add_i32 s15, s1, 0x1d000
	s_lshl_b32 s0, s0, 1
	s_add_u32 s4, s38, s0
	s_addc_u32 s5, s39, 0
	s_ashr_i32 s16, s6, 7
	v_ashrrev_i32_e32 v24, 4, v36
	s_lshl_b32 s93, s16, 4
	v_bfe_u32 v42, v36, 2, 4
	v_lshlrev_b32_e32 v0, 2, v0
	v_lshlrev_b32_e32 v32, 4, v36
	v_ashrrev_i32_e32 v25, 31, v24
	v_add_u32_e32 v12, 0x200, v36
	v_or_b32_e32 v28, s93, v42
	global_load_dword v108, v0, s[52:53]
	global_load_dword v109, v0, s[52:53] offset:64
	global_load_dword v110, v0, s[52:53] offset:128
	global_load_dword v111, v0, s[52:53] offset:192
	v_and_b32_e32 v96, 0xf0, v32
	v_lshl_add_u64 v[0:1], s[30:31], 0, v[24:25]
	v_ashrrev_i32_e32 v26, 4, v12
	v_ashrrev_i32_e32 v29, 31, v28
	v_lshl_add_u64 v[8:9], s[4:5], 0, v[96:97]
	v_lshlrev_b64 v[0:1], 13, v[0:1]
	v_ashrrev_i32_e32 v27, 31, v26
	v_lshl_add_u64 v[30:31], s[30:31], 0, v[28:29]
	v_lshl_add_u64 v[10:11], v[8:9], 0, v[0:1]
	v_lshl_add_u64 v[12:13], s[30:31], 0, v[26:27]
	v_lshlrev_b64 v[30:31], 13, v[30:31]
	s_mov_b32 s1, s87
	global_load_dwordx4 v[0:3], v[10:11], off
	global_load_dwordx4 v[4:7], v[10:11], off offset:2048
	v_add_co_u32_e32 v10, vcc, s84, v10
	v_lshlrev_b64 v[12:13], 13, v[12:13]
	v_lshl_add_u64 v[30:31], s[38:39], 0, v[30:31]
	v_addc_co_u32_e32 v11, vcc, 0, v11, vcc
	v_lshl_add_u64 v[16:17], v[8:9], 0, v[12:13]
	v_lshl_add_u64 v[30:31], v[30:31], 0, s[0:1]
	s_lshl_b32 s56, s14, 7
	s_mov_b32 s57, s87
	v_add_co_u32_e32 v20, vcc, s84, v16
	v_lshl_add_u64 v[30:31], v[30:31], 0, s[56:57]
	v_and_b32_e32 v32, 48, v32
	v_mov_b32_e32 v33, v97
	v_addc_co_u32_e32 v21, vcc, 0, v17, vcc
	v_lshl_add_u64 v[30:31], v[30:31], 0, v[32:33]
	v_lshl_add_u64 v[34:35], v[30:31], 0, s[58:59]
	v_add_co_u32_e32 v30, vcc, s84, v30
	global_load_dwordx4 v[8:11], v[10:11], off
	s_nop 0
	global_load_dwordx4 v[12:15], v[16:17], off
	v_addc_co_u32_e32 v31, vcc, 0, v31, vcc
	global_load_dwordx4 v[16:19], v[16:17], off offset:2048
	s_nop 0
	global_load_dwordx4 v[20:23], v[20:21], off
	s_nop 0
	global_load_dwordx4 v[68:71], v[30:31], off offset:2048
	global_load_dwordx4 v[56:59], v[34:35], off offset:64
	s_and_b32 s0, s6, 0x3fffff80
	v_and_b32_e32 v37, 0x7f, v36
	s_add_i32 s1, 0, 0x1c400
	s_lshl_b32 s0, s0, 2
	s_add_i32 s0, s1, s0
	v_lshlrev_b32_e32 v33, 2, v37
	v_add_u32_e32 v30, 0, v96
	v_add_u32_e32 v31, s85, v96
	v_add_u32_e32 v96, s0, v33
	s_lshl_b32 s0, s16, 5
	s_add_i32 s0, s0, 0
	v_mul_u32_u24_e32 v34, 0x48, v37
	s_cmpk_lt_u32 s6, 0x80
	v_and_b32_e32 v115, 48, v36
	v_add_u32_e32 v112, s1, v33
	v_lshl_add_u32 v114, v34, 1, s0
	s_cselect_b64 s[0:1], -1, 0
	v_mov_b32_e32 v44, s8
	v_add_u32_e32 v45, s8, v115
	s_lshl_b32 s8, s16, 6
	s_add_i32 s8, s8, 0
	s_add_i32 s92, 0, 0x1cc00
	s_andn2_b32 s6, s6, 63
	v_mul_lo_u32 v48, v24, s83
	s_add_i32 s8, s8, 0x1ce00
	s_lshl_b32 s9, s14, 8
	v_add_u32_e32 v118, s92, v33
	s_add_i32 s92, s92, s6
	v_add_u32_e32 v119, v30, v48
	v_add_u32_e32 v120, v31, v48
	v_mul_lo_u32 v48, v26, s83
	s_mul_i32 s6, s16, 0x880
	s_lshl_b32 s17, s14, 1
	s_add_i32 s91, s8, s9
	s_ashr_i32 vcc_lo, s93, 31
	s_lshl_b32 s57, s7, 4
	v_add_u32_e32 v121, v30, v48
	v_or_b32_e32 v30, s6, v37
	s_addk_i32 s6, 0x110
	v_lshlrev_b32_e32 v30, 1, v30
	s_cmp_gt_i32 s16, 0
	v_add_u32_e32 v123, 0, v30
	v_add_u32_e32 v124, s85, v30
	v_add_u32_e32 v30, s6, v37
	s_cselect_b64 s[6:7], -1, 0
	s_cmp_gt_i32 s16, 1
	v_add_u32_e32 v117, s8, v115
	s_cselect_b64 s[8:9], -1, 0
	s_cmp_gt_i32 s16, 2
	s_cselect_b64 s[10:11], -1, 0
	s_cmp_gt_i32 s16, 3
	v_lshlrev_b32_e32 v113, 2, v38
	s_cselect_b64 s[12:13], -1, 0
	s_cmp_le_i32 s17, s16
	v_or_b32_e32 v36, s93, v113
	v_lshl_add_u32 v126, v30, 1, s85
	s_cselect_b64 s[34:35], -1, 0
	v_lshl_or_b32 v30, s14, 5, v107
	s_cmp_lt_i32 s17, s16
	v_add_u32_e32 v116, 0, v115
	v_mul_u32_u24_e32 v33, 0x90, v42
	v_add_u32_e32 v122, v31, v48
	v_or_b32_e32 v31, 1, v36
	v_or_b32_e32 v49, 2, v36
	v_or_b32_e32 v50, 3, v36
	s_cselect_b64 s[96:97], -1, 0
	v_or_b32_e32 v51, 16, v30
	v_mul_u32_u24_e32 v141, 0x90, v107
	s_mov_b32 s14, 0xd000
	s_add_u32 s30, s93, s30
	v_lshl_add_u32 v46, v107, 1, s15
	v_mul_u32_u24_e32 v37, 0x110, v30
	v_mul_lo_u32 v48, v36, s88
	v_add3_u32 v140, s15, v33, v32
	v_add3_u32 v142, v116, v141, s14
	v_lshl_add_u32 v33, v30, 1, s89
	v_cmp_gt_i32_e64 s[14:15], v30, v36
	v_cmp_gt_i32_e64 s[16:17], v30, v31
	v_cmp_gt_i32_e64 s[18:19], v30, v49
	v_cmp_gt_i32_e64 s[20:21], v30, v50
	v_lshlrev_b32_e32 v30, 1, v51
	s_addc_u32 s31, vcc_lo, s31
	v_add3_u32 v143, s89, v48, v30
	v_cmp_gt_i32_e64 s[24:25], v51, v31
	v_or_b32_e32 v30, s30, v42
	v_mov_b32_e32 v31, s31
	s_lshl_b64 s[30:31], s[36:37], 26
	v_lshlrev_b64 v[28:29], 13, v[28:29]
	v_lshl_add_u64 v[28:29], s[30:31], 0, v[28:29]
	v_or3_b32 v28, v28, s56, v32
	v_lshlrev_b64 v[24:25], 13, v[24:25]
	v_lshl_add_u64 v[100:101], s[74:75], 0, v[28:29]
	v_lshl_add_u64 v[24:25], s[30:31], 0, v[24:25]
	v_lshlrev_b32_e32 v28, 4, v107
	v_or_b32_e32 v24, v24, v28
	v_lshl_add_u64 v[102:103], s[74:75], 0, v[24:25]
	v_lshlrev_b64 v[24:25], 13, v[26:27]
	v_or_b32_e32 v34, s93, v107
	v_or_b32_e32 v47, s57, v107
	v_lshl_add_u64 v[24:25], s[30:31], 0, v[24:25]
	v_mul_lo_u32 v35, v34, s83
	v_mul_lo_u32 v34, v34, s88
	v_mad_u32_u24 v43, v41, s88, 0
	v_mad_u32_u24 v44, v41, s83, v44
	v_or_b32_e32 v41, 16, v41
	v_mul_lo_u32 v47, v47, s88
	v_lshlrev_b64 v[30:31], 11, v[30:31]
	v_or_b32_e32 v24, v24, v28
	v_mul_u32_u24_e32 v40, 0x110, v107
	v_add_u32_e32 v35, 0, v35
	v_add_u32_e32 v34, s89, v34
	v_add_u32_e32 v47, 0, v47
	v_mul_u32_u24_e32 v52, 0x90, v41
	v_mul_u32_u24_e32 v41, 0x110, v41
	v_mul_u32_u24_e32 v38, 0x240, v38
	v_or3_b32 v30, v30, s56, v32
	v_lshl_add_u64 v[104:105], s[74:75], 0, v[24:25]
	v_mov_b32_e32 v24, 0
	s_waitcnt vmcnt(1)
	v_mov_b64_e32 v[60:61], v[68:69]
	s_waitcnt vmcnt(0)
	v_mov_b64_e32 v[66:67], v[58:59]
	s_movk_i32 s71, 0x7f
	v_cmp_eq_u32_e64 s[4:5], 0, v107
	v_add_u32_e32 v125, 0x110, v124
	v_add_u32_e32 v127, 0x330, v124
	v_add_u32_e32 v128, 0x440, v124
	v_add_u32_e32 v129, 0x550, v124
	v_add_u32_e32 v130, 0x660, v124
	v_add_u32_e32 v131, 0x770, v124
	v_add_u32_e32 v132, 0x880, v124
	v_add_u32_e32 v133, 0x990, v124
	v_add_u32_e32 v134, 0xaa0, v124
	v_add_u32_e32 v135, 0xbb0, v124
	v_add_u32_e32 v136, 0xcc0, v124
	v_add_u32_e32 v137, 0xdd0, v124
	v_add_u32_e32 v138, 0xee0, v124
	v_add_u32_e32 v139, 0xff0, v124
	v_cmp_gt_i32_e64 s[22:23], v51, v36
	v_add_u32_e32 v144, 0x90, v143
	v_cmp_gt_i32_e64 s[26:27], v51, v49
	v_add_u32_e32 v145, 0x120, v143
	v_cmp_gt_i32_e64 s[28:29], v51, v50
	v_add_u32_e32 v146, 0x1b0, v143
	v_lshl_add_u64 v[98:99], s[74:75], 0, v[30:31]
	v_add_u32_e32 v147, v33, v48
	v_add_u32_e32 v148, v34, v115
	v_add_u32_e32 v149, v43, v115
	v_add_u32_e32 v150, v44, v115
	v_add_u32_e32 v151, v116, v52
	v_add_u32_e32 v152, v45, v41
	v_add_u32_e32 v153, v46, v38
	v_add_u32_e32 v154, v47, v115
	v_add_u32_e32 v155, v39, v40
	v_add_u32_e32 v156, v35, v115
	v_add_u32_e32 v157, v116, v37
	v_mov_b32_e32 v25, v24
	v_mov_b32_e32 v26, v24
	v_mov_b32_e32 v27, v24
	v_mov_b32_e32 v32, v24
	v_mov_b32_e32 v33, v24
	v_mov_b32_e32 v34, v24
	v_mov_b32_e32 v35, v24
	v_mov_b32_e32 v40, v24
	v_mov_b32_e32 v41, v24
	v_mov_b32_e32 v42, v24
	v_mov_b32_e32 v43, v24
	v_mov_b32_e32 v44, v24
	v_mov_b32_e32 v45, v24
	v_mov_b32_e32 v46, v24
	v_mov_b32_e32 v47, v24
	v_mov_b32_e32 v28, v24
	v_mov_b32_e32 v29, v24
	v_mov_b32_e32 v30, v24
	v_mov_b32_e32 v31, v24
	v_mov_b32_e32 v36, v24
	v_mov_b32_e32 v37, v24
	v_mov_b32_e32 v38, v24
	v_mov_b32_e32 v39, v24
	v_mov_b32_e32 v48, v24
	v_mov_b32_e32 v49, v24
	v_mov_b32_e32 v50, v24
	v_mov_b32_e32 v51, v24
	v_mov_b32_e32 v52, v24
	v_mov_b32_e32 v53, v24
	v_mov_b32_e32 v54, v24
	v_mov_b32_e32 v55, v24
	v_mov_b64_e32 v[62:63], v[70:71]
	v_mov_b64_e32 v[64:65], v[56:57]
	s_branch .LBB0_472

.LBB0_472:
	s_and_b32 s98, s71, 7
	s_cmp_lg_u32 s98, 0
	s_cbranch_scc1 .Lhw_skip
	s_cmp_eq_u32 s71, 0
	s_cbranch_scc1 .Lhw_skip
	s_lshr_b32 s98, s71, 3
	s_sub_u32 s98, 16, s98
	s_lshl_b32 s98, s98, 6
	s_add_u32 s98, s98, 0x3800
	v_mov_b32_e32 v253, s98
	v_readfirstlane_b32 s99, v208
	s_lshr_b32 s99, s99, 6
	s_cmp_lg_u32 s99, 0
	s_cbranch_scc1 .Lspin_join_gn
	s_mov_b32 s99, 0

.Lspin_join_gn:
	s_barrier
